# adds scan V-transpose LDS image swizzle (bank-conflict-free staging writes) to the attention and FFN-down epilogue changes
# speedup vs baseline: 1.0174x; 1.0098x over previous
; __device__ __forceinline__ int opaque_tid() { int t = threadIdx.x; asm volatile("" : "+v"(t)); return t; }
; #define LAS __attribute__((address_space(3)))
; __device__ __forceinline__ void scan_phase(LAS unsigned char* lds, bf16* proj, int G, int bid) {
;     const int tid = opaque_tid(), lane = tid & 63, wave = tid >> 6, fr = lane & 15, fq = lane >> 4;
;     constexpr int KRS = 132;
;     constexpr int SET = 34304, O_KR = 0, O_QR = 8448, O_QE = 16896, O_KE = 21248, O_KD = 25600, O_DV = 33792, O_VT = 2 * SET, QST = 272;
;     const int st = tid >> 4, sc8 = tid & 15;
;     const int pdk = tid >> 2, ptq = tid & 3;
;     const bool stager = tid < 256;
;     ...
;                 const bf16x8 vf = *(const LAS bf16x8*)(lds + O_VT + (c % 3) * 8192 + (wave * 16 + fr) * 64 + fq * 16);
.LBB0_413:
	s_or_b64 exec, exec, s[0:1]
	v_readlane_b32 s0, v255, 33
	v_readlane_b32 s1, v255, 34
	s_xor_b64 s[0:1], s[0:1], -1
	v_writelane_b32 v255, s0, 46
	s_waitcnt lgkmcnt(0)
	s_barrier
	v_writelane_b32 v255, s1, 47
	s_nop 0
	v_readlane_b32 s0, v255, 39
	v_readlane_b32 s1, v255, 40
	s_and_b64 vcc, exec, s[0:1]
	s_mov_b64 s[0:1], -1
	s_cbranch_vccnz .LBB0_592
	v_readlane_b32 s4, v254, 43
	v_readlane_b32 s5, v254, 44
	s_and_b64 vcc, exec, s[4:5]
	s_cbranch_vccz .LBB0_496
	v_readlane_b32 s0, v253, 62
	v_readlane_b32 s1, v253, 63
	s_mov_b64 s[24:25], s[42:43]
	v_mov_b32_e32 v0, v209
	s_andn2_b64 vcc, exec, s[0:1]
	s_cbranch_vccnz .LBB0_444
	s_movk_i32 s0, 0x100
	v_ashrrev_i32_e32 v71, 2, v0
	v_cmp_gt_i32_e64 s[38:39], s0, v0
	s_movk_i32 s0, 0x200
	v_ashrrev_i32_e32 v70, 4, v0
	v_lshlrev_b32_e32 v72, 1, v71
	v_cmp_gt_i32_e64 s[42:43], s0, v0
	s_movk_i32 s0, 0x84
	v_and_b32_e32 v53, 15, v0
	v_add_u32_e32 v1, 0, v72
	s_waitcnt vmcnt(2)
	v_mul_lo_u32 v6, v70, s0
	v_add_u32_e32 v4, v1, v72
	v_bfe_u32 v5, v0, 4, 2
	v_lshlrev_b32_e32 v75, 2, v6
	v_lshlrev_b32_e32 v6, 5, v53
	s_waitcnt vmcnt(0)
	v_ashrrev_i32_e32 v8, 3, v0
	v_add3_u32 v76, 0, v75, v6
	v_lshlrev_b32_e32 v6, 9, v53
	v_readlane_b32 s4, v254, 11
	v_lshlrev_b32_e32 v8, 1, v8
	v_lshlrev_b32_e32 v9, 1, v70
	v_mad_u64_u32 v[54:55], s[0:1], v71, 60, v[4:5]
	v_and_b32_e32 v3, 3, v0
	v_add_u32_e32 v7, s4, v6
	v_and_b32_e32 v8, -16, v8
	v_and_b32_e32 v9, 6, v9
	s_movk_i32 s0, 0xffc4
	v_add3_u32 v77, v7, v8, v9
	v_mul_u32_u24_e32 v80, 0x210, v3
	v_mul_u32_u24_e32 v7, 0x220, v3
	v_mul_lo_u32 v84, v71, s0
	v_readlane_b32 s0, v254, 12
	v_lshl_add_u32 v81, v80, 2, v4
	v_lshl_add_u32 v82, v7, 1, v1
	v_add_u32_e32 v1, s0, v6
	v_and_b32_e32 v4, -16, v71
	v_add3_u32 v85, v1, v8, v9
	v_and_b32_e32 v204, 3, v53
	v_lshlrev_b32_e32 v204, 4, v204
	v_xor_b32_e32 v77, v77, v204
	v_xor_b32_e32 v85, v85, v204
	v_bfe_u32 v204, v53, 2, 1
	v_lshlrev_b32_e32 v204, 6, v204
	v_sub_u32_e32 v180, v77, v204
	v_sub_u32_e32 v181, v85, v204
	v_add_u32_e32 v77, v77, v204
	v_add_u32_e32 v85, v85, v204
	v_lshlrev_b32_e32 v89, 4, v5
	v_lshlrev_b32_e32 v56, 3, v5
	v_lshlrev_b32_e32 v1, 2, v5
	v_ashrrev_i32_e32 v5, 31, v4
	v_lshl_add_u64 v[4:5], v[4:5], 1, s[82:83]
	v_mov_b32_e32 v57, v2
	v_lshlrev_b32_e32 v83, 6, v71
	v_lshl_add_u64 v[58:59], v[4:5], 0, v[56:57]
	v_lshlrev_b32_e32 v4, 4, v53
	v_mov_b32_e32 v5, v2
	s_movk_i32 s0, 0x10ff
	v_cmp_lt_i32_e64 s[40:41], s22, v0
	v_lshlrev_b32_e32 v73, 4, v0
	v_lshl_add_u64 v[60:61], s[82:83], 0, v[4:5]
	v_lshlrev_b32_e32 v57, 6, v53
	v_cmp_gt_u32_e64 s[48:49], v1, v53
	v_cmp_lt_u32_e64 s[50:51], v1, v53
	v_or_b32_e32 v4, 2, v1
	v_or_b32_e32 v1, 3, v1
	v_bitop3_b32 v92, v0, s0, 15 bitop3:0x6c
	v_and_b32_e32 v0, 0xfffffc00, v83
	v_cmp_gt_u32_e64 s[54:55], v1, v53
	v_lshlrev_b32_e32 v1, 10, v3
	v_or3_b32 v0, v0, v57, v89
	v_sub_u32_e32 v74, 0xff, v70
	v_lshlrev_b32_e32 v52, 3, v53
	v_add_u32_e32 v78, 16, v70
	v_sub_u32_e32 v79, 0xef, v70
	v_cmp_eq_u32_e64 s[44:45], 0, v3
	v_cmp_lt_u32_e64 s[46:47], 1, v3
	v_lshlrev_b32_e32 v55, 4, v3
	v_add_u32_e32 v86, 32, v70
	v_sub_u32_e32 v87, 0xdf, v70
	v_mul_u32_u24_e32 v88, 0x110, v53
	v_cmp_gt_u32_e64 s[52:53], v4, v53
	v_sub_u32_e32 v90, 0, v1
	v_sub_u32_e32 v91, 0, v70
	v_lshrrev_b32_e32 v204, 5, v0
	v_and_b32_e32 v204, 0x70, v204
	v_xor_b32_e32 v0, v0, v204
	v_add_u32_e32 v93, s4, v0
	s_mov_b32 s13, s2
	s_branch .LBB0_418

; #define LAS __attribute__((address_space(3)))
; #define SC_LOAD(c_) do { const bf16* rp_ = proj + (size_t)scan_row16(b, dir, (c_), st) * HIN + h * 128 + sc8 * 8; \
;         rq = *(const u32x4*)rp_; rk = *(const u32x4*)(rp_ + kcol - h * 128); rv = *(const u32x4*)(rp_ + 3072); } while (0)
; __device__ __forceinline__ void scan_phase(LAS unsigned char* lds, bf16* proj, int G, int bid) {
;     ...
;         __syncthreads();
;         {
;             const u32x4 z4 = (u32x4){0u, 0u, 0u, 0u};
;             for (int o_ = tid * 16; o_ < 8192; o_ += NTHR * 16) { *(LAS u32x4*)(lds + O_KD + o_) = z4; *(LAS u32x4*)(lds + SET + O_KD + o_) = z4; *(LAS u32x4*)(lds + O_VT + o_) = z4; *(LAS u32x4*)(lds + O_VT + 8192 + o_) = z4; *(LAS u32x4*)(lds + O_VT + 16384 + o_) = z4; }
;         }
;         if (stager) SC_LOAD(0);
;         __syncthreads();
;         if (stager) { SC_WRITE(0); SC_LOAD(1); }
;         __syncthreads();
;         SC_PREP(0);
;         if (stager) { SC_WRITE(1); SC_LOAD(2); }
.LBB0_423:
	s_or_b64 exec, exec, s[4:5]
	s_waitcnt lgkmcnt(0)
	s_barrier
	s_and_saveexec_b64 s[4:5], s[38:39]
	s_cbranch_execz .LBB0_425
	s_cmp_eq_u32 s15, 0
	s_cselect_b64 vcc, -1, 0
	s_lshl_b32 s6, s14, 8
	s_add_i32 s6, s6, 0x10000
	v_cndmask_b32_e32 v0, v79, v78, vcc
	v_add_u32_e32 v3, s6, v0
	v_mov_b64_e32 v[0:1], s[82:83]
	v_mad_i64_i32 v[0:1], s[6:7], v3, s3, v[0:1]
	s_lshl_b32 s6, s0, 1
	s_mov_b32 s7, s72
	v_lshl_add_u64 v[0:1], v[0:1], 0, s[6:7]
	v_mov_b32_e32 v17, v2
	s_add_i32 s7, s1, s0
	s_waitcnt vmcnt(1)
	v_lshlrev_b32_e32 v18, 16, v12
	v_and_b32_e32 v19, 0xffff0000, v12
	v_lshlrev_b32_e32 v22, 16, v4
	v_and_b32_e32 v23, 0xffff0000, v4
	v_lshlrev_b32_e32 v20, 16, v13
	v_and_b32_e32 v21, 0xffff0000, v13
	v_lshlrev_b32_e32 v24, 16, v5
	v_and_b32_e32 v25, 0xffff0000, v5
	v_lshl_add_u64 v[0:1], v[0:1], 0, v[16:17]
	s_lshl_b32 s16, s7, 1
	s_mov_b32 s17, s72
	s_waitcnt vmcnt(0)
	ds_write_b16 v77, v8
	ds_write_b16_d16_hi v180, v8 offset:64
	ds_write_b128 v76, v[18:21]
	ds_write_b128 v76, v[22:25] offset:8448
	ds_write_b16 v77, v9 offset:128
	ds_write_b16_d16_hi v180, v9 offset:192
	v_lshl_add_u64 v[8:9], v[0:1], 0, s[16:17]
	v_lshlrev_b32_e32 v12, 16, v14
	v_and_b32_e32 v13, 0xffff0000, v14
	v_lshlrev_b32_e32 v4, 16, v6
	v_and_b32_e32 v5, 0xffff0000, v6
	v_lshlrev_b32_e32 v14, 16, v15
	v_and_b32_e32 v15, 0xffff0000, v15
	v_lshlrev_b32_e32 v6, 16, v7
	v_and_b32_e32 v7, 0xffff0000, v7
	v_subrev_co_u32_e32 v8, vcc, s6, v8
	ds_write_b16 v77, v10 offset:256
	ds_write_b16_d16_hi v180, v10 offset:320
	ds_write_b128 v76, v[12:15] offset:16
	ds_write_b128 v76, v[4:7] offset:8464
	ds_write_b16 v77, v11 offset:384
	ds_write_b16_d16_hi v180, v11 offset:448
	v_subbrev_co_u32_e32 v9, vcc, 0, v9, vcc
	global_load_dwordx4 v[4:7], v[0:1], off
	global_load_dwordx4 v[12:15], v[8:9], off offset:2048
	v_add_co_u32_e32 v0, vcc, 0x1000, v0
	s_nop 1
	v_addc_co_u32_e32 v1, vcc, 0, v1, vcc
	global_load_dwordx4 v[8:11], v[0:1], off offset:2048
.LBB0_425:
	s_or_b64 exec, exec, s[4:5]
	s_waitcnt lgkmcnt(0)
	s_barrier
	ds_read2_b32 v[18:19], v81 offset1:132
	v_add_u32_e32 v0, 0x2000, v81
	ds_read2_b32 v[20:21], v0 offset0:64 offset1:196
	v_add_u32_e32 v0, 0x400, v81
	ds_read2_b32 v[22:23], v0 offset0:8 offset1:140
	v_add_u32_e32 v0, 0x2400, v81
	ds_read2_b32 v[24:25], v0 offset0:72 offset1:204
	s_waitcnt lgkmcnt(3)
	v_sub_f32_e32 v0, 1.0, v18
	v_max_f32_e32 v1, 0x3bdb8bac, v0
	v_sub_f32_e32 v0, 1.0, v19
	v_max_f32_e32 v0, 0x3bdb8bac, v0
	v_mul_f32_e32 v3, v1, v0
	s_waitcnt lgkmcnt(1)
	v_sub_f32_e32 v0, 1.0, v22
	v_max_f32_e32 v0, 0x3bdb8bac, v0
	v_mul_f32_e32 v17, v3, v0
	v_sub_f32_e32 v0, 1.0, v23
	v_max_f32_e32 v0, 0x3bdb8bac, v0
	v_mul_f32_e32 v28, v17, v0
	s_nop 1
	v_mul_f32_dpp v0, v28, v28 quad_perm:[0,0,1,2] row_mask:0xf bank_mask:0xf bound_ctrl:1
	v_cndmask_b32_e64 v0, v0, v28, s[44:45]
	s_nop 1
	v_mul_f32_dpp v26, v0, v0 quad_perm:[0,0,0,1] row_mask:0xf bank_mask:0xf bound_ctrl:1
	v_cndmask_b32_e64 v26, v0, v26, s[46:47]
	v_mov_b32_e32 v0, v2
	s_nop 1
	v_mov_b32_dpp v0, v26 quad_perm:[0,0,1,2] row_mask:0xf bank_mask:0xf
	v_cndmask_b32_e64 v29, v0, 1.0, s[44:45]
	v_mov_b32_e32 v0, v2
	v_mul_f32_e32 v1, v1, v29
	s_nop 0
	v_mov_b32_dpp v0, v26 quad_perm:[3,3,3,3] row_mask:0xf bank_mask:0xf
	v_rcp_f32_e32 v26, v1
	v_mul_f32_e32 v1, v20, v1
	v_cvt_pk_bf16_f32 v1, v1, s0
	ds_write_b16 v82, v1 offset:16896
	v_mul_f32_e32 v1, v3, v29
	v_rcp_f32_e32 v27, v1
	v_mul_f32_e32 v1, v21, v1
	v_cvt_pk_bf16_f32 v1, v1, s0
	ds_write_b16 v82, v1 offset:17168
	v_mul_f32_e32 v1, v17, v29
	v_rcp_f32_e32 v20, v1
	s_waitcnt lgkmcnt(2)
	v_mul_f32_e32 v1, v24, v1
	v_cvt_pk_bf16_f32 v1, v1, s0
	ds_write_b16 v82, v1 offset:17440
	v_mul_f32_e32 v1, v28, v29
	v_rcp_f32_e32 v21, v1
	v_mul_f32_e32 v1, v25, v1
	v_cvt_pk_bf16_f32 v1, v1, s0
	v_pk_mul_f32 v[18:19], v[18:19], v[26:27]
	ds_write_b16 v82, v1 offset:17712
	v_cvt_pk_bf16_f32 v1, v18, s0
	ds_write_b16 v82, v1 offset:21248
	v_pk_mul_f32 v[24:25], v[18:19], v[0:1] op_sel_hi:[1,0]
	v_cvt_pk_bf16_f32 v1, v19, s0
	v_pk_mul_f32 v[20:21], v[22:23], v[20:21]
	ds_write_b16 v82, v1 offset:21520
	v_cvt_pk_bf16_f32 v1, v20, s0
	ds_write_b16 v82, v1 offset:21792
	v_pk_mul_f32 v[22:23], v[20:21], v[0:1] op_sel_hi:[1,0]
	v_cvt_pk_bf16_f32 v1, v21, s0
	v_cvt_pk_bf16_f32 v18, v24, v25
	ds_write_b16 v82, v1 offset:22064
	v_cvt_pk_bf16_f32 v19, v22, v23
	v_add_u32_e32 v1, v54, v55
	ds_write_b64 v1, v[18:19] offset:25600
	s_and_saveexec_b64 s[4:5], s[44:45]
	v_readlane_b32 s74, v254, 33
	v_readlane_b32 s75, v254, 34
	v_add_u32_e32 v1, v54, v84
	ds_write_b32 v1, v0 offset:33792
	s_or_b64 exec, exec, s[4:5]
	s_add_i32 s16, s1, s0
	s_add_i32 s4, s16, 0x400
	s_mov_b32 s1, s72
	s_mov_b32 s5, s72
	v_mov_b64_e32 v[18:19], s[4:5]
	v_mov_b64_e32 v[0:1], s[0:1]
	s_and_saveexec_b64 s[18:19], s[40:41]
	s_xor_b64 s[34:35], exec, s[18:19]
	s_lshl_b32 s6, s14, 8
	s_add_i32 s17, s6, 0x10000
	s_sub_u32 s6, 0, s0
	s_subb_u32 s7, 0, 0
	v_mov_b64_e32 v[18:19], s[4:5]
	v_mov_b64_e32 v[0:1], s[0:1]
	s_or_saveexec_b64 s[4:5], s[34:35]
	v_mov_b64_e32 v[62:63], s[6:7]
	v_mov_b32_e32 v94, s17
	s_xor_b64 exec, exec, s[4:5]
	s_cbranch_execz .LBB0_431
	s_cmp_eq_u32 s15, 0
	s_cselect_b64 vcc, -1, 0
	s_lshl_b32 s1, s14, 8
	s_waitcnt vmcnt(1)
	v_lshlrev_b32_e32 v20, 16, v12
	v_and_b32_e32 v21, 0xffff0000, v12
	v_lshlrev_b32_e32 v24, 16, v4
	v_and_b32_e32 v25, 0xffff0000, v4
	v_lshlrev_b32_e32 v22, 16, v13
	v_and_b32_e32 v23, 0xffff0000, v13
	v_lshlrev_b32_e32 v26, 16, v5
	v_and_b32_e32 v27, 0xffff0000, v5
	v_lshlrev_b32_e32 v12, 16, v14
	v_and_b32_e32 v13, 0xffff0000, v14
	v_lshlrev_b32_e32 v4, 16, v6
	v_and_b32_e32 v5, 0xffff0000, v6
	v_lshlrev_b32_e32 v14, 16, v15
	v_and_b32_e32 v15, 0xffff0000, v15
	v_lshlrev_b32_e32 v6, 16, v7
	v_and_b32_e32 v7, 0xffff0000, v7
	s_add_i32 s18, s1, 0x10000
	v_cndmask_b32_e32 v1, v87, v86, vcc
	s_waitcnt vmcnt(0)
	ds_write_b16 v85, v8
	ds_write_b16_d16_hi v181, v8 offset:64
	ds_write_b128 v76, v[20:23] offset:34304
	ds_write_b128 v76, v[24:27] offset:42752
	ds_write_b16 v85, v9 offset:128
	ds_write_b16_d16_hi v181, v9 offset:192
	ds_write_b16 v85, v10 offset:256
	ds_write_b16_d16_hi v181, v10 offset:320
	ds_write_b128 v76, v[12:15] offset:34320
	ds_write_b128 v76, v[4:7] offset:42768
	ds_write_b16 v85, v11 offset:384
	ds_write_b16_d16_hi v181, v11 offset:448
	v_add_u32_e32 v1, s18, v1
	v_mov_b64_e32 v[4:5], s[82:83]
	v_mad_i64_i32 v[4:5], s[6:7], v1, s3, v[4:5]
	s_lshl_b32 s6, s0, 1
	s_mov_b32 s7, s72
	v_lshl_add_u64 v[4:5], v[4:5], 0, s[6:7]
	v_mov_b32_e32 v17, v2
	v_lshl_add_u64 v[8:9], v[4:5], 0, v[16:17]
	s_lshl_b32 s16, s16, 1
	s_mov_b32 s17, s72
	v_lshl_add_u64 v[10:11], v[8:9], 0, s[16:17]
	v_subrev_co_u32_e32 v10, vcc, s6, v10
	global_load_dwordx4 v[4:7], v[8:9], off
	s_nop 0
	v_subbrev_co_u32_e32 v11, vcc, 0, v11, vcc
	global_load_dwordx4 v[12:15], v[10:11], off offset:2048
	v_add_co_u32_e32 v8, vcc, 0x1000, v8
	s_sub_u32 s0, 0, s0
	s_nop 0
	v_addc_co_u32_e32 v9, vcc, 0, v9, vcc
	global_load_dwordx4 v[8:11], v[8:9], off offset:2048
	s_subb_u32 s1, 0, 0
	v_mov_b64_e32 v[62:63], s[0:1]
	v_mov_b32_e32 v94, s18

; #define SC_LOAD(c_) do { const bf16* rp_ = proj + (size_t)scan_row16(b, dir, (c_), st) * HIN + h * 128 + sc8 * 8; \
;         rq = *(const u32x4*)rp_; rk = *(const u32x4*)(rp_ + kcol - h * 128); rv = *(const u32x4*)(rp_ + 3072); } while (0)
; __device__ __forceinline__ void scan_phase(LAS unsigned char* lds, bf16* proj, int G, int bid) {
;     ...
;                     u32x2 ow; ow.x = cvt_pk_bf16(oacc[0], oacc[1]); ow.y = cvt_pk_bf16(oacc[2], oacc[3]);
;                     *(u32x2*)(proj + (size_t)scan_row16(b, dir, c, fr) * HIN + kcol + wave * 16 + fq * 4) = ow;
;                 }
;             }
;             if (stager) { if (c + 2 < 272) SC_WRITE(c + 2); if (c + 3 < 272) SC_LOAD(c + 3); }
.LBB0_439:
	s_nop 0
	v_cvt_pk_bf16_f32 v48, v48, v49
	v_cvt_pk_bf16_f32 v49, v50, v51
	v_mad_i64_i32 v[0:1], s[0:1], v0, s3, v[66:67]
	global_store_dwordx2 v[0:1], v[48:49], off
	s_and_saveexec_b64 s[0:1], s[38:39]
	s_cbranch_execz .LBB0_432
	s_cmpk_gt_u32 s6, 0x10d
	s_cbranch_scc1 .LBB0_442
	v_lshlrev_b32_e32 v0, 2, v52
	v_add3_u32 v0, s14, v75, v0
	s_add_i32 s14, s6, 2
	s_and_b32 s15, s14, 0xffff
	s_mul_i32 s15, s15, 0xaaab
	s_lshr_b32 s15, s15, 17
	s_mul_i32 s15, s15, 3
	s_sub_i32 s14, s14, s15
	s_and_b32 s14, s14, 0xffff
	v_lshl_add_u32 v1, s14, 13, v77
	v_lshl_add_u32 v205, s14, 13, v180
	s_waitcnt vmcnt(2)
	v_lshlrev_b32_e32 v48, 16, v12
	v_and_b32_e32 v49, 0xffff0000, v12
	v_lshlrev_b32_e32 v98, 16, v4
	v_and_b32_e32 v99, 0xffff0000, v4
	v_lshlrev_b32_e32 v50, 16, v13
	v_and_b32_e32 v51, 0xffff0000, v13
	v_lshlrev_b32_e32 v100, 16, v5
	v_and_b32_e32 v101, 0xffff0000, v5
	s_waitcnt vmcnt(1)
	ds_write_b16 v1, v8
	ds_write_b16_d16_hi v205, v8 offset:64
	ds_write_b128 v0, v[48:51]
	ds_write_b128 v0, v[98:101] offset:8448
	ds_write_b16 v1, v9 offset:128
	ds_write_b16_d16_hi v205, v9 offset:192
	v_lshlrev_b32_e32 v48, 16, v14
	v_and_b32_e32 v49, 0xffff0000, v14
	v_lshlrev_b32_e32 v98, 16, v6
	v_and_b32_e32 v99, 0xffff0000, v6
	v_lshlrev_b32_e32 v50, 16, v15
	v_and_b32_e32 v51, 0xffff0000, v15
	v_lshlrev_b32_e32 v100, 16, v7
	v_and_b32_e32 v101, 0xffff0000, v7
	ds_write_b16 v1, v10 offset:256
	ds_write_b16_d16_hi v205, v10 offset:320
	ds_write_b128 v0, v[48:51] offset:16
	ds_write_b128 v0, v[98:101] offset:8464
	ds_write_b16 v1, v11 offset:384
	ds_write_b16_d16_hi v205, v11 offset:448
